# speedup vs baseline: 1.0192x; 1.0035x over previous
.LBB0_164:
	v_mov_b32_e32 v14, v0
	v_mov_b32_e32 v15, v0
	v_sub_u32_e32 v231, v1, v130
	v_mov_b32_e32 v1, v0
	v_mov_b32_e32 v2, v0
	v_mov_b32_e32 v3, v0
	v_mov_b32_e32 v4, v0
	v_mov_b32_e32 v5, v0
	v_mov_b32_e32 v6, v0
	v_mov_b32_e32 v7, v0
	v_mov_b32_e32 v8, v0
	v_mov_b32_e32 v9, v0
	v_mov_b32_e32 v10, v0
	v_mov_b32_e32 v11, v0
	v_mov_b32_e32 v12, v0
	v_mov_b32_e32 v13, v0
	v_mov_b64_e32 v[64:65], v[14:15]
	v_mov_b64_e32 v[48:49], v[14:15]
	v_mov_b64_e32 v[32:33], v[14:15]
	s_lshl_b32 s33, s10, 1
	v_mov_b64_e32 v[62:63], v[12:13]
	v_mov_b64_e32 v[60:61], v[10:11]
	v_mov_b64_e32 v[58:59], v[8:9]
	v_mov_b64_e32 v[56:57], v[6:7]
	v_mov_b64_e32 v[54:55], v[4:5]
	v_mov_b64_e32 v[52:53], v[2:3]
	v_mov_b64_e32 v[50:51], v[0:1]
	v_mov_b64_e32 v[46:47], v[12:13]
	v_mov_b64_e32 v[44:45], v[10:11]
	v_mov_b64_e32 v[42:43], v[8:9]
	v_mov_b64_e32 v[40:41], v[6:7]
	v_mov_b64_e32 v[38:39], v[4:5]
	v_mov_b64_e32 v[36:37], v[2:3]
	v_mov_b64_e32 v[34:35], v[0:1]
	v_mov_b64_e32 v[30:31], v[12:13]
	v_mov_b64_e32 v[28:29], v[10:11]
	v_mov_b64_e32 v[26:27], v[8:9]
	v_mov_b64_e32 v[24:25], v[6:7]
	v_mov_b64_e32 v[22:23], v[4:5]
	v_mov_b64_e32 v[20:21], v[2:3]
	v_mov_b64_e32 v[18:19], v[0:1]
	v_mov_b64_e32 v[16:17], v[14:15]
	s_xor_b64 s[2:3], s[8:9], -1
	s_add_i32 s79, s33, 2
	s_mov_b32 s99, 0
	v_mov_b32_e32 v233, 0xf149f2ca
	v_mov_b32_e32 v232, 0
	s_movk_i32 s98, 0xff
	v_mov_b64_e32 v[200:201], v[198:199]
	v_mov_b64_e32 v[14:15], v[12:13]
	v_mov_b64_e32 v[12:13], v[10:11]
	v_mov_b64_e32 v[10:11], v[8:9]
	v_mov_b64_e32 v[8:9], v[6:7]
	v_mov_b64_e32 v[6:7], v[4:5]
	v_mov_b64_e32 v[4:5], v[2:3]
	v_mov_b64_e32 v[2:3], v[0:1]
	s_waitcnt lgkmcnt(0)
	s_barrier
	ds_read_b128 v[66:69], v225
	ds_read_b128 v[70:73], v226
	ds_read_b128 v[74:77], v227
	ds_read_b128 v[78:81], v228
	ds_read_b128 v[212:215], v225 offset:8192
	ds_read_b128 v[250:253], v226 offset:8192
	s_cmp_lt_u32 s97, 64
	s_cbranch_scc1 .Lattn_prio_skip
	s_setprio 2

.LBB0_166:
.LBB0_167:
.LBB0_169:
	s_add_i32 s8, s98, 0xffffff40
	s_cmp_le_i32 s8, s74
	s_waitcnt lgkmcnt(5)
	v_mfma_f32_32x32x16_bf16 v[82:97], v[66:69], v[98:101], 0
	s_waitcnt lgkmcnt(4)
	v_mfma_f32_32x32x16_bf16 v[82:97], v[70:73], v[102:105], v[82:97]
	s_waitcnt lgkmcnt(3)
	v_mfma_f32_32x32x16_bf16 v[82:97], v[74:77], v[106:109], v[82:97]
	s_waitcnt lgkmcnt(2)
	v_mfma_f32_32x32x16_bf16 v[82:97], v[78:81], v[110:113], v[82:97]
	s_waitcnt lgkmcnt(1)
	v_mfma_f32_32x32x16_bf16 v[66:81], v[212:215], v[98:101], 0
	ds_read_b128 v[212:215], v227 offset:8192
	s_waitcnt lgkmcnt(1)
	v_mfma_f32_32x32x16_bf16 v[66:81], v[250:253], v[102:105], v[66:81]
	ds_read_b128 v[250:253], v228 offset:8192
	s_waitcnt lgkmcnt(1)
	v_mfma_f32_32x32x16_bf16 v[66:81], v[212:215], v[106:109], v[66:81]
	s_waitcnt lgkmcnt(0)
	v_mfma_f32_32x32x16_bf16 v[66:81], v[250:253], v[110:113], v[66:81]
	s_cbranch_scc1 .LBB0_171
	v_cmp_gt_i32_e64 s[68:69], 26, v231
	v_cmp_gt_i32_e64 s[70:71], 27, v231
	v_cmp_gt_i32_e64 s[66:67], 25, v231
	s_and_b64 s[68:69], s[70:71], s[68:69]
	v_cmp_gt_i32_e64 s[64:65], 24, v231
	s_and_b64 s[66:67], s[68:69], s[66:67]
	v_cmp_gt_i32_e64 s[62:63], 19, v231
	s_and_b64 s[64:65], s[66:67], s[64:65]
	v_cmp_gt_i32_e64 s[60:61], 18, v231
	s_and_b64 s[62:63], s[64:65], s[62:63]
	v_cmp_gt_i32_e64 s[58:59], 17, v231
	s_and_b64 s[60:61], s[62:63], s[60:61]
	v_cmp_gt_i32_e64 s[56:57], 16, v231
	s_and_b64 s[58:59], s[60:61], s[58:59]
	v_cmp_gt_i32_e64 s[54:55], 11, v231
	s_and_b64 s[56:57], s[58:59], s[56:57]
	v_cmp_gt_i32_e64 s[52:53], 10, v231
	s_and_b64 s[54:55], s[56:57], s[54:55]
	v_cmp_gt_i32_e64 s[50:51], 9, v231
	s_and_b64 s[52:53], s[54:55], s[52:53]
	v_cmp_gt_i32_e64 s[48:49], 8, v231
	s_and_b64 s[50:51], s[52:53], s[50:51]
	v_cmp_gt_i32_e64 s[46:47], 3, v231
	s_and_b64 s[48:49], s[50:51], s[48:49]
	v_cmp_gt_i32_e64 s[44:45], 2, v231
	s_and_b64 s[46:47], s[48:49], s[46:47]
	v_cmp_gt_i32_e64 s[42:43], 1, v231
	s_and_b64 s[44:45], s[46:47], s[44:45]
	v_cmp_gt_i32_e64 s[40:41], 0, v231
	s_and_b64 s[42:43], s[44:45], s[42:43]
	s_and_b64 s[40:41], s[42:43], s[40:41]
	v_cmp_gt_i32_e64 s[36:37], 58, v231
	v_cndmask_b32_e64 v82, v82, v210, s[40:41]
	v_cmp_gt_i32_e64 s[40:41], 59, v231
	v_cmp_gt_i32_e64 s[34:35], 57, v231
	s_and_b64 s[36:37], s[40:41], s[36:37]
	v_cmp_gt_i32_e64 s[30:31], 56, v231
	s_and_b64 s[34:35], s[36:37], s[34:35]
	v_cmp_gt_i32_e64 s[28:29], 51, v231
	s_and_b64 s[30:31], s[34:35], s[30:31]
	v_cmp_gt_i32_e64 s[26:27], 50, v231
	s_and_b64 s[28:29], s[30:31], s[28:29]
	v_cmp_gt_i32_e64 s[24:25], 49, v231
	s_and_b64 s[26:27], s[28:29], s[26:27]
	v_cmp_gt_i32_e64 s[22:23], 48, v231
	s_and_b64 s[24:25], s[26:27], s[24:25]
	v_cmp_gt_i32_e64 s[20:21], 43, v231
	s_and_b64 s[22:23], s[24:25], s[22:23]
	v_cmp_gt_i32_e64 s[18:19], 42, v231
	s_and_b64 s[20:21], s[22:23], s[20:21]
	v_cmp_gt_i32_e64 s[16:17], 41, v231
	s_and_b64 s[18:19], s[20:21], s[18:19]
	v_cmp_gt_i32_e64 s[14:15], 40, v231
	s_and_b64 s[16:17], s[18:19], s[16:17]
	v_cmp_gt_i32_e64 s[12:13], 35, v231
	s_and_b64 s[14:15], s[16:17], s[14:15]
	v_cmp_gt_i32_e64 s[10:11], 34, v231
	s_and_b64 s[12:13], s[14:15], s[12:13]
	v_cmp_gt_i32_e64 s[8:9], 33, v231
	s_and_b64 s[10:11], s[12:13], s[10:11]
	v_cmp_gt_i32_e32 vcc, 32, v231
	s_and_b64 s[8:9], s[10:11], s[8:9]
	s_and_b64 vcc, s[8:9], vcc
	v_cndmask_b32_e64 v97, v97, v210, s[70:71]
	v_cndmask_b32_e64 v96, v96, v210, s[68:69]
	v_cndmask_b32_e64 v95, v95, v210, s[66:67]
	v_cndmask_b32_e64 v94, v94, v210, s[64:65]
	v_cndmask_b32_e64 v93, v93, v210, s[62:63]
	v_cndmask_b32_e64 v92, v92, v210, s[60:61]
	v_cndmask_b32_e64 v91, v91, v210, s[58:59]
	v_cndmask_b32_e64 v90, v90, v210, s[56:57]
	v_cndmask_b32_e64 v89, v89, v210, s[54:55]
	v_cndmask_b32_e64 v88, v88, v210, s[52:53]
	v_cndmask_b32_e64 v87, v87, v210, s[50:51]
	v_cndmask_b32_e64 v86, v86, v210, s[48:49]
	v_cndmask_b32_e64 v85, v85, v210, s[46:47]
	v_cndmask_b32_e64 v84, v84, v210, s[44:45]
	v_cndmask_b32_e64 v83, v83, v210, s[42:43]
	v_cndmask_b32_e64 v81, v81, v210, s[40:41]
	v_cndmask_b32_e64 v80, v80, v210, s[36:37]
	v_cndmask_b32_e64 v79, v79, v210, s[34:35]
	v_cndmask_b32_e64 v78, v78, v210, s[30:31]
	v_cndmask_b32_e64 v77, v77, v210, s[28:29]
	v_cndmask_b32_e64 v76, v76, v210, s[26:27]
	v_cndmask_b32_e64 v75, v75, v210, s[24:25]
	v_cndmask_b32_e64 v74, v74, v210, s[22:23]
	v_cndmask_b32_e64 v73, v73, v210, s[20:21]
	v_cndmask_b32_e64 v72, v72, v210, s[18:19]
	v_cndmask_b32_e64 v71, v71, v210, s[16:17]
	v_cndmask_b32_e64 v70, v70, v210, s[14:15]
	v_cndmask_b32_e64 v69, v69, v210, s[12:13]
	v_cndmask_b32_e64 v68, v68, v210, s[10:11]
	v_cndmask_b32_e64 v67, v67, v210, s[8:9]
	v_cndmask_b32_e32 v66, v66, v210, vcc
.LBB0_171:
	s_nop 1
	v_max_f32_e32 v1, v83, v83
	v_max_f32_e32 v206, v82, v82
	v_max_f32_e32 v1, v206, v1
	v_max3_f32 v1, v1, v84, v85
	v_max3_f32 v1, v1, v86, v87
	v_max3_f32 v1, v1, v88, v89
	v_max3_f32 v1, v1, v90, v91
	v_max3_f32 v1, v1, v92, v93
	v_max3_f32 v1, v1, v94, v95
	v_max3_f32 v1, v1, v96, v97
	v_max3_f32 v1, v1, v66, v67
	v_max3_f32 v1, v1, v68, v69
	v_max3_f32 v1, v1, v70, v71
	v_max3_f32 v1, v1, v72, v73
	v_max3_f32 v1, v1, v74, v75
	v_max3_f32 v1, v1, v76, v77
	v_max3_f32 v1, v1, v78, v79
	v_max3_f32 v1, v1, v80, v81
	v_mov_b32_e32 v206, v1
	s_nop 1
	v_permlane32_swap_b32_e32 v1, v206
	v_max_f32_e32 v206, v206, v206
	v_max_f32_e32 v1, v1, v1
	v_max_f32_e32 v1, v1, v206
	v_sub_f32_e32 v206, v1, v233
	v_mul_f32_e32 v206, 0x3e000000, v206
	v_cmp_ge_f32_e32 vcc, s85, v206
	v_max_f32_e32 v206, v233, v233
	v_max_f32_e32 v234, v206, v1
	v_sub_f32_e32 v1, v233, v234
	v_mul_f32_e32 v1, 0x3e38aa3b, v1
	v_exp_f32_e32 v1, v1
	s_cmp_eq_u64 vcc, exec
	s_cselect_b64 s[8:9], -1, 0
	v_cndmask_b32_e64 v1, v1, 1.0, s[8:9]
	v_cmp_gt_f32_e32 vcc, 1.0, v1
	s_cbranch_vccz .LBB0_175
	s_and_saveexec_b64 s[10:11], s[4:5]
	ds_write_b32 v159, v1 offset:128
	s_or_b64 exec, exec, s[10:11]
	s_waitcnt lgkmcnt(0)
	ds_read_b128 v[212:215], v161 offset:224
	ds_read_b128 v[236:239], v161 offset:192
	ds_read_b128 v[240:243], v161 offset:160
	ds_read_b128 v[244:247], v161 offset:128
	s_waitcnt lgkmcnt(3)
	v_pk_mul_f32 v[64:65], v[64:65], v[214:215]
	s_waitcnt lgkmcnt(2)
	v_pk_mul_f32 v[60:61], v[60:61], v[238:239]
	s_waitcnt lgkmcnt(1)
	v_pk_mul_f32 v[56:57], v[56:57], v[242:243]
	s_waitcnt lgkmcnt(0)
	v_pk_mul_f32 v[52:53], v[52:53], v[246:247]
	v_pk_mul_f32 v[62:63], v[62:63], v[212:213]
	v_pk_mul_f32 v[58:59], v[58:59], v[236:237]
	v_pk_mul_f32 v[54:55], v[54:55], v[240:241]
	v_pk_mul_f32 v[50:51], v[50:51], v[244:245]
	v_pk_mul_f32 v[48:49], v[48:49], v[214:215]
	v_pk_mul_f32 v[44:45], v[44:45], v[238:239]
	v_pk_mul_f32 v[40:41], v[40:41], v[242:243]
	v_pk_mul_f32 v[36:37], v[36:37], v[246:247]
	v_pk_mul_f32 v[46:47], v[46:47], v[212:213]
	v_pk_mul_f32 v[42:43], v[42:43], v[236:237]
	v_pk_mul_f32 v[38:39], v[38:39], v[240:241]
	v_pk_mul_f32 v[34:35], v[34:35], v[244:245]
	v_pk_mul_f32 v[32:33], v[32:33], v[214:215]
	v_pk_mul_f32 v[28:29], v[28:29], v[238:239]
	v_pk_mul_f32 v[24:25], v[24:25], v[242:243]
	v_pk_mul_f32 v[20:21], v[20:21], v[246:247]
	v_pk_mul_f32 v[30:31], v[30:31], v[212:213]
	v_pk_mul_f32 v[26:27], v[26:27], v[236:237]
	v_pk_mul_f32 v[22:23], v[22:23], v[240:241]
	v_pk_mul_f32 v[18:19], v[18:19], v[244:245]
	v_pk_mul_f32 v[16:17], v[16:17], v[214:215]
	v_pk_mul_f32 v[12:13], v[12:13], v[238:239]
	v_pk_mul_f32 v[8:9], v[8:9], v[242:243]
	v_pk_mul_f32 v[4:5], v[4:5], v[246:247]
	v_pk_mul_f32 v[14:15], v[14:15], v[212:213]
	v_pk_mul_f32 v[10:11], v[10:11], v[236:237]
	v_pk_mul_f32 v[6:7], v[6:7], v[240:241]
	v_pk_mul_f32 v[2:3], v[2:3], v[244:245]
.LBB0_175:
	v_cndmask_b32_e64 v233, v234, v233, s[8:9]
	v_mul_f32_e32 v206, 0xbe38aa3b, v233
	v_fmamk_f32 v82, v82, 0x3e38aa3b, v206
	v_fmamk_f32 v83, v83, 0x3e38aa3b, v206
	v_fmamk_f32 v84, v84, 0x3e38aa3b, v206
	v_fmamk_f32 v85, v85, 0x3e38aa3b, v206
	v_fmamk_f32 v86, v86, 0x3e38aa3b, v206
	v_fmamk_f32 v87, v87, 0x3e38aa3b, v206
	v_fmamk_f32 v88, v88, 0x3e38aa3b, v206
	v_fmamk_f32 v89, v89, 0x3e38aa3b, v206
	v_fmamk_f32 v90, v90, 0x3e38aa3b, v206
	v_fmamk_f32 v91, v91, 0x3e38aa3b, v206
	v_fmamk_f32 v92, v92, 0x3e38aa3b, v206
	v_fmamk_f32 v93, v93, 0x3e38aa3b, v206
	v_fmamk_f32 v94, v94, 0x3e38aa3b, v206
	v_fmamk_f32 v95, v95, 0x3e38aa3b, v206
	v_fmamk_f32 v96, v96, 0x3e38aa3b, v206
	v_fmamk_f32 v97, v97, 0x3e38aa3b, v206
	v_fmamk_f32 v66, v66, 0x3e38aa3b, v206
	v_fmamk_f32 v67, v67, 0x3e38aa3b, v206
	v_fmamk_f32 v68, v68, 0x3e38aa3b, v206
	v_fmamk_f32 v69, v69, 0x3e38aa3b, v206
	v_fmamk_f32 v70, v70, 0x3e38aa3b, v206
	v_fmamk_f32 v71, v71, 0x3e38aa3b, v206
	v_fmamk_f32 v72, v72, 0x3e38aa3b, v206
	v_fmamk_f32 v73, v73, 0x3e38aa3b, v206
	v_fmamk_f32 v74, v74, 0x3e38aa3b, v206
	v_fmamk_f32 v75, v75, 0x3e38aa3b, v206
	v_fmamk_f32 v76, v76, 0x3e38aa3b, v206
	v_fmamk_f32 v77, v77, 0x3e38aa3b, v206
	v_fmamk_f32 v78, v78, 0x3e38aa3b, v206
	v_fmamk_f32 v79, v79, 0x3e38aa3b, v206
	v_fmamk_f32 v80, v80, 0x3e38aa3b, v206
	v_fmac_f32_e32 v206, 0x3e38aa3b, v81
	v_exp_f32_e32 v81, v82
	v_exp_f32_e32 v82, v83
	v_exp_f32_e32 v83, v84
	v_exp_f32_e32 v84, v85
	v_exp_f32_e32 v85, v86
	v_exp_f32_e32 v86, v87
	v_exp_f32_e32 v87, v88
	v_exp_f32_e32 v88, v89
	v_exp_f32_e32 v89, v90
	v_exp_f32_e32 v90, v91
	v_exp_f32_e32 v91, v92
	v_exp_f32_e32 v92, v93
	v_exp_f32_e32 v93, v94
	v_exp_f32_e32 v94, v95
	v_exp_f32_e32 v95, v96
	v_exp_f32_e32 v96, v97
	v_exp_f32_e32 v97, v66
	v_add_f32_e32 v66, 0, v81
	v_add_f32_e32 v66, v82, v66
	v_add_f32_e32 v66, v83, v66
	v_add_f32_e32 v66, v84, v66
	v_add_f32_e32 v66, v85, v66
	v_add_f32_e32 v66, v86, v66
	v_add_f32_e32 v66, v87, v66
	v_add_f32_e32 v66, v88, v66
	v_add_f32_e32 v66, v89, v66
	v_add_f32_e32 v66, v90, v66
	v_add_f32_e32 v66, v91, v66
	v_add_f32_e32 v66, v92, v66
	v_add_f32_e32 v66, v93, v66
	v_exp_f32_e32 v212, v67
	v_add_f32_e32 v66, v94, v66
	v_exp_f32_e32 v213, v68
	v_add_f32_e32 v66, v95, v66
	v_exp_f32_e32 v214, v69
	v_add_f32_e32 v66, v96, v66
	v_exp_f32_e32 v215, v70
	v_add_f32_e32 v66, v97, v66
	v_exp_f32_e32 v236, v71
	v_add_f32_e32 v66, v212, v66
	v_exp_f32_e32 v237, v72
	v_add_f32_e32 v66, v213, v66
	v_exp_f32_e32 v238, v73
	v_add_f32_e32 v66, v214, v66
	v_exp_f32_e32 v239, v74
	v_add_f32_e32 v66, v215, v66
	v_exp_f32_e32 v240, v75
	v_add_f32_e32 v66, v236, v66
	v_exp_f32_e32 v241, v76
	v_add_f32_e32 v66, v237, v66
	v_exp_f32_e32 v242, v77
	v_add_f32_e32 v66, v238, v66
	v_exp_f32_e32 v243, v78
	v_add_f32_e32 v66, v239, v66
	v_exp_f32_e32 v244, v79
	v_add_f32_e32 v66, v240, v66
	v_exp_f32_e32 v245, v80
	v_add_f32_e32 v66, v241, v66
	v_exp_f32_e32 v206, v206
	v_add_f32_e32 v66, v242, v66
	v_add_f32_e32 v66, v243, v66
	v_add_f32_e32 v66, v244, v66
	v_add_f32_e32 v66, v245, v66
	v_add_f32_e32 v234, v206, v66
	v_mov_b32_e32 v235, v234
	s_nop 1
	v_permlane32_swap_b32_e32 v234, v235
	v_cvt_pk_bf16_f32 v66, v81, v82
	v_cvt_pk_bf16_f32 v67, v83, v84
	v_cvt_pk_bf16_f32 v68, v85, v86
	v_cvt_pk_bf16_f32 v69, v87, v88
	v_cvt_pk_bf16_f32 v70, v89, v90
	v_cvt_pk_bf16_f32 v71, v91, v92
	v_cvt_pk_bf16_f32 v72, v93, v94
	v_cvt_pk_bf16_f32 v73, v95, v96
	v_cvt_pk_bf16_f32 v74, v97, v212
	ds_read_b64_tr_b16 v[82:83], v153 offset:0
	ds_read_b64_tr_b16 v[84:85], v153 offset:0x800
	ds_read_b64_tr_b16 v[86:87], v153 offset:0x1000
	ds_read_b64_tr_b16 v[88:89], v153 offset:0x1800
	ds_read_b64_tr_b16 v[90:91], v153 offset:0x2000
	ds_read_b64_tr_b16 v[92:93], v153 offset:0x2800
	ds_read_b64_tr_b16 v[94:95], v153 offset:0x3000
	ds_read_b64_tr_b16 v[96:97], v153 offset:0x3800
	v_cvt_pk_bf16_f32 v75, v213, v214
	v_cvt_pk_bf16_f32 v76, v215, v236
	v_cvt_pk_bf16_f32 v77, v237, v238
	v_cvt_pk_bf16_f32 v78, v239, v240
	v_cvt_pk_bf16_f32 v79, v241, v242
	v_cvt_pk_bf16_f32 v80, v243, v244
	v_cvt_pk_bf16_f32 v81, v245, v206
	s_nop 0
	v_permlane32_swap_b32_e32 v66, v68
	v_permlane32_swap_b32_e32 v67, v69
	v_permlane32_swap_b32_e32 v70, v72
	v_permlane32_swap_b32_e32 v71, v73
	v_permlane32_swap_b32_e32 v74, v76
	v_permlane32_swap_b32_e32 v75, v77
	v_permlane32_swap_b32_e32 v78, v80
	v_permlane32_swap_b32_e32 v79, v81
	s_nop 0
	s_waitcnt lgkmcnt(6)
	v_mfma_f32_32x32x16_bf16 v[50:65], v[66:69], v[82:85], v[50:65]
	ds_read_b64_tr_b16 v[82:83], v153 offset:0x200
	ds_read_b64_tr_b16 v[84:85], v153 offset:0xa00
	s_waitcnt lgkmcnt(6)
	v_mfma_f32_32x32x16_bf16 v[50:65], v[70:73], v[86:89], v[50:65]
	ds_read_b64_tr_b16 v[86:87], v153 offset:0x1200
	ds_read_b64_tr_b16 v[88:89], v153 offset:0x1a00
	s_waitcnt lgkmcnt(6)
	v_mfma_f32_32x32x16_bf16 v[50:65], v[74:77], v[90:93], v[50:65]
	ds_read_b64_tr_b16 v[90:91], v153 offset:0x2200
	ds_read_b64_tr_b16 v[92:93], v153 offset:0x2a00
	s_waitcnt lgkmcnt(6)
	v_mfma_f32_32x32x16_bf16 v[50:65], v[78:81], v[94:97], v[50:65]
	s_andn2_b64 vcc, exec, s[38:39]
	s_cbranch_vccnz .Lattn_sw0
	v_add_u32_e32 v250, s84, v157
	s_waitcnt vmcnt(3)
	ds_write_b128 v224, v[114:117] offset:32768
	s_waitcnt vmcnt(1)
	ds_write_b128 v224, v[122:125] offset:40960
	ds_write_b128 v250, v[118:121]
	v_add_u32_e32 v250, s84, v155
	s_waitcnt vmcnt(0)
	ds_write_b128 v250, v[126:129]

.Lattn_sl0:
	ds_read_b64_tr_b16 v[94:95], v153 offset:0x3200
	ds_read_b64_tr_b16 v[96:97], v153 offset:0x3a00
	s_waitcnt lgkmcnt(6)
	v_mfma_f32_32x32x16_bf16 v[34:49], v[66:69], v[82:85], v[34:49]
	ds_read_b64_tr_b16 v[82:83], v153 offset:0x400
	ds_read_b64_tr_b16 v[84:85], v153 offset:0xc00
	s_waitcnt lgkmcnt(6)
	v_mfma_f32_32x32x16_bf16 v[34:49], v[70:73], v[86:89], v[34:49]
	ds_read_b64_tr_b16 v[86:87], v153 offset:0x1400
	ds_read_b64_tr_b16 v[88:89], v153 offset:0x1c00
	s_waitcnt lgkmcnt(6)
	v_mfma_f32_32x32x16_bf16 v[34:49], v[74:77], v[90:93], v[34:49]
	ds_read_b64_tr_b16 v[90:91], v153 offset:0x2400
	ds_read_b64_tr_b16 v[92:93], v153 offset:0x2c00
	s_waitcnt lgkmcnt(6)
	v_mfma_f32_32x32x16_bf16 v[34:49], v[78:81], v[94:97], v[34:49]
	ds_read_b64_tr_b16 v[94:95], v153 offset:0x3400
	ds_read_b64_tr_b16 v[96:97], v153 offset:0x3c00
	s_waitcnt lgkmcnt(6)
	v_mfma_f32_32x32x16_bf16 v[18:33], v[66:69], v[82:85], v[18:33]
	ds_read_b64_tr_b16 v[82:83], v153 offset:0x600
	ds_read_b64_tr_b16 v[84:85], v153 offset:0xe00
	s_waitcnt lgkmcnt(6)
	v_mfma_f32_32x32x16_bf16 v[18:33], v[70:73], v[86:89], v[18:33]
	ds_read_b64_tr_b16 v[86:87], v153 offset:0x1600
	ds_read_b64_tr_b16 v[88:89], v153 offset:0x1e00
	s_waitcnt lgkmcnt(6)
	v_mfma_f32_32x32x16_bf16 v[18:33], v[74:77], v[90:93], v[18:33]
	ds_read_b64_tr_b16 v[90:91], v153 offset:0x2600
	ds_read_b64_tr_b16 v[92:93], v153 offset:0x2e00
	s_waitcnt lgkmcnt(6)
	v_mfma_f32_32x32x16_bf16 v[18:33], v[78:81], v[94:97], v[18:33]
	ds_read_b64_tr_b16 v[94:95], v153 offset:0x3600
	ds_read_b64_tr_b16 v[96:97], v153 offset:0x3e00
	s_waitcnt lgkmcnt(6)
	v_mfma_f32_32x32x16_bf16 v[2:17], v[66:69], v[82:85], v[2:17]
	s_andn2_b64 vcc, exec, s[72:73]
	ds_read_b128 v[66:69], v225 offset:16384
	s_waitcnt lgkmcnt(5)
	v_mfma_f32_32x32x16_bf16 v[2:17], v[70:73], v[86:89], v[2:17]
	ds_read_b128 v[70:73], v226 offset:16384
	s_waitcnt lgkmcnt(4)
	v_mfma_f32_32x32x16_bf16 v[2:17], v[74:77], v[90:93], v[2:17]
	ds_read_b128 v[74:77], v227 offset:16384
	s_waitcnt lgkmcnt(3)
	v_mfma_f32_32x32x16_bf16 v[2:17], v[78:81], v[94:97], v[2:17]
	ds_read_b128 v[78:81], v228 offset:16384
	ds_read_b128 v[212:215], v225 offset:24576
	ds_read_b128 v[250:253], v226 offset:24576
.LBB0_179:
	s_add_i32 s8, s98, 0xffffff80
	s_cmp_le_i32 s8, s74
	s_waitcnt lgkmcnt(5)
	v_mfma_f32_32x32x16_bf16 v[82:97], v[66:69], v[98:101], 0
	s_waitcnt lgkmcnt(4)
	v_mfma_f32_32x32x16_bf16 v[82:97], v[70:73], v[102:105], v[82:97]
	s_waitcnt lgkmcnt(3)
	v_mfma_f32_32x32x16_bf16 v[82:97], v[74:77], v[106:109], v[82:97]
	s_waitcnt lgkmcnt(2)
	v_mfma_f32_32x32x16_bf16 v[82:97], v[78:81], v[110:113], v[82:97]
	s_waitcnt lgkmcnt(1)
	v_mfma_f32_32x32x16_bf16 v[66:81], v[212:215], v[98:101], 0
	ds_read_b128 v[212:215], v227 offset:24576
	s_waitcnt lgkmcnt(1)
	v_mfma_f32_32x32x16_bf16 v[66:81], v[250:253], v[102:105], v[66:81]
	ds_read_b128 v[250:253], v228 offset:24576
	s_waitcnt lgkmcnt(1)
	v_mfma_f32_32x32x16_bf16 v[66:81], v[212:215], v[106:109], v[66:81]
	s_waitcnt lgkmcnt(0)
	v_mfma_f32_32x32x16_bf16 v[66:81], v[250:253], v[110:113], v[66:81]
	s_cbranch_scc1 .LBB0_181
	v_subrev_u32_e32 v206, 64, v231
	v_cmp_gt_i32_e64 s[68:69], 26, v206
	v_cmp_gt_i32_e64 s[70:71], 27, v206
	v_cmp_gt_i32_e64 s[66:67], 25, v206
	s_and_b64 s[68:69], s[70:71], s[68:69]
	v_cmp_gt_i32_e64 s[64:65], 24, v206
	s_and_b64 s[66:67], s[68:69], s[66:67]
	v_cmp_gt_i32_e64 s[62:63], 19, v206
	s_and_b64 s[64:65], s[66:67], s[64:65]
	v_cmp_gt_i32_e64 s[60:61], 18, v206
	s_and_b64 s[62:63], s[64:65], s[62:63]
	v_cmp_gt_i32_e64 s[58:59], 17, v206
	s_and_b64 s[60:61], s[62:63], s[60:61]
	v_cmp_gt_i32_e64 s[56:57], 16, v206
	s_and_b64 s[58:59], s[60:61], s[58:59]
	v_cmp_gt_i32_e64 s[54:55], 11, v206
	s_and_b64 s[56:57], s[58:59], s[56:57]
	v_cmp_gt_i32_e64 s[52:53], 10, v206
	s_and_b64 s[54:55], s[56:57], s[54:55]
	v_cmp_gt_i32_e64 s[50:51], 9, v206
	s_and_b64 s[52:53], s[54:55], s[52:53]
	v_cmp_gt_i32_e64 s[48:49], 8, v206
	s_and_b64 s[50:51], s[52:53], s[50:51]
	v_cmp_gt_i32_e64 s[46:47], 3, v206
	s_and_b64 s[48:49], s[50:51], s[48:49]
	v_cmp_gt_i32_e64 s[44:45], 2, v206
	s_and_b64 s[46:47], s[48:49], s[46:47]
	v_cmp_gt_i32_e64 s[42:43], 1, v206
	s_and_b64 s[44:45], s[46:47], s[44:45]
	v_cmp_gt_i32_e64 s[40:41], 0, v206
	s_and_b64 s[42:43], s[44:45], s[42:43]
	s_and_b64 s[40:41], s[42:43], s[40:41]
	v_cmp_gt_i32_e64 s[36:37], 58, v206
	v_cndmask_b32_e64 v82, v82, v210, s[40:41]
	v_cmp_gt_i32_e64 s[40:41], 59, v206
	v_cmp_gt_i32_e64 s[34:35], 57, v206
	s_and_b64 s[36:37], s[40:41], s[36:37]
	v_cmp_gt_i32_e64 s[30:31], 56, v206
	s_and_b64 s[34:35], s[36:37], s[34:35]
	v_cmp_gt_i32_e64 s[28:29], 51, v206
	s_and_b64 s[30:31], s[34:35], s[30:31]
	v_cmp_gt_i32_e64 s[26:27], 50, v206
	s_and_b64 s[28:29], s[30:31], s[28:29]
	v_cmp_gt_i32_e64 s[24:25], 49, v206
	s_and_b64 s[26:27], s[28:29], s[26:27]
	v_cmp_gt_i32_e64 s[22:23], 48, v206
	s_and_b64 s[24:25], s[26:27], s[24:25]
	v_cmp_gt_i32_e64 s[20:21], 43, v206
	s_and_b64 s[22:23], s[24:25], s[22:23]
	v_cmp_gt_i32_e64 s[18:19], 42, v206
	s_and_b64 s[20:21], s[22:23], s[20:21]
	v_cmp_gt_i32_e64 s[16:17], 41, v206
	s_and_b64 s[18:19], s[20:21], s[18:19]
	v_cmp_gt_i32_e64 s[14:15], 40, v206
	s_and_b64 s[16:17], s[18:19], s[16:17]
	v_cmp_gt_i32_e64 s[12:13], 35, v206
	s_and_b64 s[14:15], s[16:17], s[14:15]
	v_cmp_gt_i32_e64 s[10:11], 34, v206
	s_and_b64 s[12:13], s[14:15], s[12:13]
	v_cmp_gt_i32_e64 s[8:9], 33, v206
	s_and_b64 s[10:11], s[12:13], s[10:11]
	v_cmp_gt_i32_e32 vcc, 32, v206
	s_and_b64 s[8:9], s[10:11], s[8:9]
	s_and_b64 vcc, s[8:9], vcc
	v_cndmask_b32_e64 v97, v97, v210, s[70:71]
	v_cndmask_b32_e64 v96, v96, v210, s[68:69]
	v_cndmask_b32_e64 v95, v95, v210, s[66:67]
	v_cndmask_b32_e64 v94, v94, v210, s[64:65]
	v_cndmask_b32_e64 v93, v93, v210, s[62:63]
	v_cndmask_b32_e64 v92, v92, v210, s[60:61]
	v_cndmask_b32_e64 v91, v91, v210, s[58:59]
	v_cndmask_b32_e64 v90, v90, v210, s[56:57]
	v_cndmask_b32_e64 v89, v89, v210, s[54:55]
	v_cndmask_b32_e64 v88, v88, v210, s[52:53]
	v_cndmask_b32_e64 v87, v87, v210, s[50:51]
	v_cndmask_b32_e64 v86, v86, v210, s[48:49]
	v_cndmask_b32_e64 v85, v85, v210, s[46:47]
	v_cndmask_b32_e64 v84, v84, v210, s[44:45]
	v_cndmask_b32_e64 v83, v83, v210, s[42:43]
	v_cndmask_b32_e64 v81, v81, v210, s[40:41]
	v_cndmask_b32_e64 v80, v80, v210, s[36:37]
	v_cndmask_b32_e64 v79, v79, v210, s[34:35]
	v_cndmask_b32_e64 v78, v78, v210, s[30:31]
	v_cndmask_b32_e64 v77, v77, v210, s[28:29]
	v_cndmask_b32_e64 v76, v76, v210, s[26:27]
	v_cndmask_b32_e64 v75, v75, v210, s[24:25]
	v_cndmask_b32_e64 v74, v74, v210, s[22:23]
	v_cndmask_b32_e64 v73, v73, v210, s[20:21]
	v_cndmask_b32_e64 v72, v72, v210, s[18:19]
	v_cndmask_b32_e64 v71, v71, v210, s[16:17]
	v_cndmask_b32_e64 v70, v70, v210, s[14:15]
	v_cndmask_b32_e64 v69, v69, v210, s[12:13]
	v_cndmask_b32_e64 v68, v68, v210, s[10:11]
	v_cndmask_b32_e64 v67, v67, v210, s[8:9]
	v_cndmask_b32_e32 v66, v66, v210, vcc
.LBB0_181:
	s_nop 1
	v_max_f32_e32 v206, v83, v83
	v_max_f32_e32 v212, v82, v82
	v_max_f32_e32 v206, v212, v206
	v_max3_f32 v206, v206, v84, v85
	v_max3_f32 v206, v206, v86, v87
	v_max3_f32 v206, v206, v88, v89
	v_max3_f32 v206, v206, v90, v91
	v_max3_f32 v206, v206, v92, v93
	v_max3_f32 v206, v206, v94, v95
	v_max3_f32 v206, v206, v96, v97
	v_max3_f32 v206, v206, v66, v67
	v_max3_f32 v206, v206, v68, v69
	v_max3_f32 v206, v206, v70, v71
	v_max3_f32 v206, v206, v72, v73
	v_max3_f32 v206, v206, v74, v75
	v_max3_f32 v206, v206, v76, v77
	v_max3_f32 v206, v206, v78, v79
	v_max3_f32 v206, v206, v80, v81
	v_mov_b32_e32 v212, v206
	s_nop 1
	v_permlane32_swap_b32_e32 v206, v212
	v_max_f32_e32 v212, v212, v212
	v_max_f32_e32 v206, v206, v206
	v_max_f32_e32 v206, v206, v212
	v_sub_f32_e32 v212, v206, v233
	v_mul_f32_e32 v212, 0x3e000000, v212
	v_cmp_ge_f32_e32 vcc, s85, v212
	v_max_f32_e32 v212, v233, v233
	v_max_f32_e32 v237, v212, v206
	v_sub_f32_e32 v206, v233, v237
	v_mul_f32_e32 v206, 0x3e38aa3b, v206
	v_exp_f32_e32 v206, v206
	s_cmp_eq_u64 vcc, exec
	s_cselect_b64 s[8:9], -1, 0
	v_cndmask_b32_e64 v236, v206, 1.0, s[8:9]
	v_cmp_gt_f32_e32 vcc, 1.0, v236
	s_cbranch_vccz .LBB0_185
	s_and_saveexec_b64 s[10:11], s[4:5]
	ds_write_b32 v159, v236 offset:128
	s_or_b64 exec, exec, s[10:11]
	s_waitcnt lgkmcnt(0)
	ds_read_b128 v[212:215], v161 offset:224
	ds_read_b128 v[238:241], v161 offset:192
	ds_read_b128 v[242:245], v161 offset:160
	ds_read_b128 v[246:249], v161 offset:128
	s_waitcnt lgkmcnt(3)
	v_pk_mul_f32 v[64:65], v[64:65], v[214:215]
	s_waitcnt lgkmcnt(2)
	v_pk_mul_f32 v[60:61], v[60:61], v[240:241]
	s_waitcnt lgkmcnt(1)
	v_pk_mul_f32 v[56:57], v[56:57], v[244:245]
	s_waitcnt lgkmcnt(0)
	v_pk_mul_f32 v[52:53], v[52:53], v[248:249]
	v_pk_mul_f32 v[62:63], v[62:63], v[212:213]
	v_pk_mul_f32 v[58:59], v[58:59], v[238:239]
	v_pk_mul_f32 v[54:55], v[54:55], v[242:243]
	v_pk_mul_f32 v[50:51], v[50:51], v[246:247]
	v_pk_mul_f32 v[48:49], v[48:49], v[214:215]
	v_pk_mul_f32 v[44:45], v[44:45], v[240:241]
	v_pk_mul_f32 v[40:41], v[40:41], v[244:245]
	v_pk_mul_f32 v[36:37], v[36:37], v[248:249]
	v_pk_mul_f32 v[46:47], v[46:47], v[212:213]
	v_pk_mul_f32 v[42:43], v[42:43], v[238:239]
	v_pk_mul_f32 v[38:39], v[38:39], v[242:243]
	v_pk_mul_f32 v[34:35], v[34:35], v[246:247]
	v_pk_mul_f32 v[32:33], v[32:33], v[214:215]
	v_pk_mul_f32 v[28:29], v[28:29], v[240:241]
	v_pk_mul_f32 v[24:25], v[24:25], v[244:245]
	v_pk_mul_f32 v[20:21], v[20:21], v[248:249]
	v_pk_mul_f32 v[30:31], v[30:31], v[212:213]
	v_pk_mul_f32 v[26:27], v[26:27], v[238:239]
	v_pk_mul_f32 v[22:23], v[22:23], v[242:243]
	v_pk_mul_f32 v[18:19], v[18:19], v[246:247]
	v_pk_mul_f32 v[16:17], v[16:17], v[214:215]
	v_pk_mul_f32 v[12:13], v[12:13], v[240:241]
	v_pk_mul_f32 v[8:9], v[8:9], v[244:245]
	v_pk_mul_f32 v[4:5], v[4:5], v[248:249]
	v_pk_mul_f32 v[14:15], v[14:15], v[212:213]
	v_pk_mul_f32 v[10:11], v[10:11], v[238:239]
	v_pk_mul_f32 v[6:7], v[6:7], v[242:243]
	v_pk_mul_f32 v[2:3], v[2:3], v[246:247]
.LBB0_185:
	v_cndmask_b32_e64 v233, v237, v233, s[8:9]
	v_mul_f32_e32 v206, 0xbe38aa3b, v233
	v_fmamk_f32 v82, v82, 0x3e38aa3b, v206
	v_fmamk_f32 v83, v83, 0x3e38aa3b, v206
	v_fmamk_f32 v84, v84, 0x3e38aa3b, v206
	v_fmamk_f32 v85, v85, 0x3e38aa3b, v206
	v_fmamk_f32 v86, v86, 0x3e38aa3b, v206
	v_fmamk_f32 v87, v87, 0x3e38aa3b, v206
	v_fmamk_f32 v88, v88, 0x3e38aa3b, v206
	v_fmamk_f32 v89, v89, 0x3e38aa3b, v206
	v_fmamk_f32 v90, v90, 0x3e38aa3b, v206
	v_fmamk_f32 v91, v91, 0x3e38aa3b, v206
	v_fmamk_f32 v92, v92, 0x3e38aa3b, v206
	v_fmamk_f32 v93, v93, 0x3e38aa3b, v206
	v_fmamk_f32 v94, v94, 0x3e38aa3b, v206
	v_fmamk_f32 v95, v95, 0x3e38aa3b, v206
	v_fmamk_f32 v96, v96, 0x3e38aa3b, v206
	v_fmamk_f32 v97, v97, 0x3e38aa3b, v206
	v_fmamk_f32 v66, v66, 0x3e38aa3b, v206
	v_fmamk_f32 v67, v67, 0x3e38aa3b, v206
	v_fmamk_f32 v68, v68, 0x3e38aa3b, v206
	v_fmamk_f32 v69, v69, 0x3e38aa3b, v206
	v_fmamk_f32 v70, v70, 0x3e38aa3b, v206
	v_fmamk_f32 v71, v71, 0x3e38aa3b, v206
	v_fmamk_f32 v72, v72, 0x3e38aa3b, v206
	v_fmamk_f32 v73, v73, 0x3e38aa3b, v206
	v_fmamk_f32 v74, v74, 0x3e38aa3b, v206
	v_fmamk_f32 v75, v75, 0x3e38aa3b, v206
	v_fmamk_f32 v76, v76, 0x3e38aa3b, v206
	v_fmamk_f32 v77, v77, 0x3e38aa3b, v206
	v_fmamk_f32 v78, v78, 0x3e38aa3b, v206
	v_fmamk_f32 v79, v79, 0x3e38aa3b, v206
	v_fmamk_f32 v80, v80, 0x3e38aa3b, v206
	v_fmac_f32_e32 v206, 0x3e38aa3b, v81
	v_exp_f32_e32 v81, v82
	v_exp_f32_e32 v82, v83
	v_exp_f32_e32 v83, v84
	v_exp_f32_e32 v84, v85
	v_exp_f32_e32 v85, v86
	v_exp_f32_e32 v86, v87
	v_exp_f32_e32 v87, v88
	v_exp_f32_e32 v88, v89
	v_exp_f32_e32 v89, v90
	v_exp_f32_e32 v90, v91
	v_exp_f32_e32 v91, v92
	v_exp_f32_e32 v92, v93
	v_exp_f32_e32 v93, v94
	v_exp_f32_e32 v94, v95
	v_exp_f32_e32 v95, v96
	v_exp_f32_e32 v96, v97
	v_add_f32_e32 v97, v234, v235
	v_fmac_f32_e32 v97, v232, v1
	v_exp_f32_e32 v1, v66
	v_add_f32_e32 v66, 0, v81
	v_add_f32_e32 v66, v82, v66
	v_add_f32_e32 v66, v83, v66
	v_add_f32_e32 v66, v84, v66
	v_add_f32_e32 v66, v85, v66
	v_add_f32_e32 v66, v86, v66
	v_add_f32_e32 v66, v87, v66
	v_add_f32_e32 v66, v88, v66
	v_add_f32_e32 v66, v89, v66
	v_add_f32_e32 v66, v90, v66
	v_add_f32_e32 v66, v91, v66
	v_add_f32_e32 v66, v92, v66
	v_add_f32_e32 v66, v93, v66
	v_exp_f32_e32 v212, v67
	v_add_f32_e32 v66, v94, v66
	v_exp_f32_e32 v213, v68
	v_add_f32_e32 v66, v95, v66
	v_exp_f32_e32 v214, v69
	v_add_f32_e32 v66, v96, v66
	v_exp_f32_e32 v215, v70
	v_add_f32_e32 v66, v1, v66
	v_exp_f32_e32 v234, v71
	v_add_f32_e32 v66, v212, v66
	v_exp_f32_e32 v235, v72
	v_add_f32_e32 v66, v213, v66
	v_exp_f32_e32 v237, v73
	v_add_f32_e32 v66, v214, v66
	v_exp_f32_e32 v238, v74
	v_add_f32_e32 v66, v215, v66
	v_exp_f32_e32 v239, v75
	v_add_f32_e32 v66, v234, v66
	v_exp_f32_e32 v240, v76
	v_add_f32_e32 v66, v235, v66
	v_exp_f32_e32 v241, v77
	v_add_f32_e32 v66, v237, v66
	v_exp_f32_e32 v242, v78
	v_add_f32_e32 v66, v238, v66
	v_exp_f32_e32 v243, v79
	v_add_f32_e32 v66, v239, v66
	v_exp_f32_e32 v244, v80
	v_add_f32_e32 v66, v240, v66
	v_exp_f32_e32 v206, v206
	v_add_f32_e32 v66, v241, v66
	v_add_f32_e32 v66, v242, v66
	v_add_f32_e32 v66, v243, v66
	v_add_f32_e32 v66, v244, v66
	v_add_f32_e32 v66, v206, v66
	v_mov_b32_e32 v67, v66
	s_nop 1
	v_permlane32_swap_b32_e32 v66, v67
	v_add_f32_e32 v232, v66, v67
	v_fmac_f32_e32 v232, v97, v236
	v_cvt_pk_bf16_f32 v66, v81, v82
	v_cvt_pk_bf16_f32 v67, v83, v84
	v_cvt_pk_bf16_f32 v68, v85, v86
	v_cvt_pk_bf16_f32 v69, v87, v88
	v_cvt_pk_bf16_f32 v70, v89, v90
	v_cvt_pk_bf16_f32 v71, v91, v92
	v_cvt_pk_bf16_f32 v72, v93, v94
	v_cvt_pk_bf16_f32 v73, v95, v96
	ds_read_b64_tr_b16 v[82:83], v153 offset:0x4000
	ds_read_b64_tr_b16 v[84:85], v153 offset:0x4800
	ds_read_b64_tr_b16 v[86:87], v153 offset:0x5000
	ds_read_b64_tr_b16 v[88:89], v153 offset:0x5800
	ds_read_b64_tr_b16 v[90:91], v153 offset:0x6000
	ds_read_b64_tr_b16 v[92:93], v153 offset:0x6800
	ds_read_b64_tr_b16 v[94:95], v153 offset:0x7000
	ds_read_b64_tr_b16 v[96:97], v153 offset:0x7800
	v_cvt_pk_bf16_f32 v74, v1, v212
	v_cvt_pk_bf16_f32 v75, v213, v214
	v_cvt_pk_bf16_f32 v76, v215, v234
	v_cvt_pk_bf16_f32 v77, v235, v237
	v_cvt_pk_bf16_f32 v78, v238, v239
	v_cvt_pk_bf16_f32 v79, v240, v241
	v_cvt_pk_bf16_f32 v80, v242, v243
	v_cvt_pk_bf16_f32 v81, v244, v206
	s_nop 0
	v_permlane32_swap_b32_e32 v66, v68
	v_permlane32_swap_b32_e32 v67, v69
	v_permlane32_swap_b32_e32 v70, v72
	v_permlane32_swap_b32_e32 v71, v73
	v_permlane32_swap_b32_e32 v74, v76
	v_permlane32_swap_b32_e32 v75, v77
	v_permlane32_swap_b32_e32 v78, v80
	v_permlane32_swap_b32_e32 v79, v81
	s_nop 0
	s_waitcnt lgkmcnt(6)
	v_mfma_f32_32x32x16_bf16 v[50:65], v[66:69], v[82:85], v[50:65]
	ds_read_b64_tr_b16 v[82:83], v153 offset:0x4200
	ds_read_b64_tr_b16 v[84:85], v153 offset:0x4a00
	s_waitcnt lgkmcnt(6)
	v_mfma_f32_32x32x16_bf16 v[50:65], v[70:73], v[86:89], v[50:65]
	ds_read_b64_tr_b16 v[86:87], v153 offset:0x5200
	ds_read_b64_tr_b16 v[88:89], v153 offset:0x5a00
	s_waitcnt lgkmcnt(6)
	v_mfma_f32_32x32x16_bf16 v[50:65], v[74:77], v[90:93], v[50:65]
	ds_read_b64_tr_b16 v[90:91], v153 offset:0x6200
	ds_read_b64_tr_b16 v[92:93], v153 offset:0x6a00
	s_waitcnt lgkmcnt(6)
	v_mfma_f32_32x32x16_bf16 v[50:65], v[78:81], v[94:97], v[50:65]
	s_andn2_b64 vcc, exec, s[72:73]
	s_cbranch_vccnz .Lattn_sw1
	v_add_u32_e32 v250, s88, v157
	s_waitcnt vmcnt(3)
	ds_write_b128 v224, v[114:117] offset:49152
	s_waitcnt vmcnt(1)
	ds_write_b128 v224, v[122:125] offset:57344
	ds_write_b128 v250, v[118:121]
	v_add_u32_e32 v250, s88, v155
	s_waitcnt vmcnt(0)
	ds_write_b128 v250, v[126:129]

.Lattn_sl1:
	ds_read_b64_tr_b16 v[94:95], v153 offset:0x7200
	ds_read_b64_tr_b16 v[96:97], v153 offset:0x7a00
	s_waitcnt lgkmcnt(6)
	v_mfma_f32_32x32x16_bf16 v[34:49], v[66:69], v[82:85], v[34:49]
	ds_read_b64_tr_b16 v[82:83], v153 offset:0x4400
	ds_read_b64_tr_b16 v[84:85], v153 offset:0x4c00
	s_waitcnt lgkmcnt(6)
	v_mfma_f32_32x32x16_bf16 v[34:49], v[70:73], v[86:89], v[34:49]
	ds_read_b64_tr_b16 v[86:87], v153 offset:0x5400
	ds_read_b64_tr_b16 v[88:89], v153 offset:0x5c00
	s_waitcnt lgkmcnt(6)
	v_mfma_f32_32x32x16_bf16 v[34:49], v[74:77], v[90:93], v[34:49]
	ds_read_b64_tr_b16 v[90:91], v153 offset:0x6400
	ds_read_b64_tr_b16 v[92:93], v153 offset:0x6c00
	s_waitcnt lgkmcnt(6)
	v_mfma_f32_32x32x16_bf16 v[34:49], v[78:81], v[94:97], v[34:49]
	ds_read_b64_tr_b16 v[94:95], v153 offset:0x7400
	ds_read_b64_tr_b16 v[96:97], v153 offset:0x7c00
	s_waitcnt lgkmcnt(6)
	v_mfma_f32_32x32x16_bf16 v[18:33], v[66:69], v[82:85], v[18:33]
	ds_read_b64_tr_b16 v[82:83], v153 offset:0x4600
	ds_read_b64_tr_b16 v[84:85], v153 offset:0x4e00
	s_waitcnt lgkmcnt(6)
	v_mfma_f32_32x32x16_bf16 v[18:33], v[70:73], v[86:89], v[18:33]
	ds_read_b64_tr_b16 v[86:87], v153 offset:0x5600
	ds_read_b64_tr_b16 v[88:89], v153 offset:0x5e00
	s_waitcnt lgkmcnt(6)
	v_mfma_f32_32x32x16_bf16 v[18:33], v[74:77], v[90:93], v[18:33]
	ds_read_b64_tr_b16 v[90:91], v153 offset:0x6600
	ds_read_b64_tr_b16 v[92:93], v153 offset:0x6e00
	s_waitcnt lgkmcnt(6)
	v_mfma_f32_32x32x16_bf16 v[18:33], v[78:81], v[94:97], v[18:33]
	ds_read_b64_tr_b16 v[94:95], v153 offset:0x7600
	ds_read_b64_tr_b16 v[96:97], v153 offset:0x7e00
	s_waitcnt lgkmcnt(6)
	v_mfma_f32_32x32x16_bf16 v[2:17], v[66:69], v[82:85], v[2:17]
	s_andn2_b64 vcc, exec, s[38:39]
	s_waitcnt lgkmcnt(0)
	s_barrier
	ds_read_b128 v[66:69], v225 offset:32768
	v_mfma_f32_32x32x16_bf16 v[2:17], v[70:73], v[86:89], v[2:17]
	ds_read_b128 v[70:73], v226 offset:32768
	v_mfma_f32_32x32x16_bf16 v[2:17], v[74:77], v[90:93], v[2:17]
	ds_read_b128 v[74:77], v227 offset:32768
	v_mfma_f32_32x32x16_bf16 v[2:17], v[78:81], v[94:97], v[2:17]
	ds_read_b128 v[78:81], v228 offset:32768
	ds_read_b128 v[212:215], v225 offset:40960
	ds_read_b128 v[250:253], v226 offset:40960
	s_cbranch_vccnz .LBB0_207
.LBB0_190:
	s_sub_i32 s8, s98, 64
	s_cmp_le_i32 s8, s74
	s_waitcnt lgkmcnt(5)
	v_mfma_f32_32x32x16_bf16 v[82:97], v[66:69], v[98:101], 0
	s_waitcnt lgkmcnt(4)
	v_mfma_f32_32x32x16_bf16 v[82:97], v[70:73], v[102:105], v[82:97]
	s_waitcnt lgkmcnt(3)
	v_mfma_f32_32x32x16_bf16 v[82:97], v[74:77], v[106:109], v[82:97]
	s_waitcnt lgkmcnt(2)
	v_mfma_f32_32x32x16_bf16 v[82:97], v[78:81], v[110:113], v[82:97]
	s_waitcnt lgkmcnt(1)
	v_mfma_f32_32x32x16_bf16 v[66:81], v[212:215], v[98:101], 0
	ds_read_b128 v[212:215], v227 offset:40960
	s_waitcnt lgkmcnt(1)
	v_mfma_f32_32x32x16_bf16 v[66:81], v[250:253], v[102:105], v[66:81]
	ds_read_b128 v[250:253], v228 offset:40960
	s_waitcnt lgkmcnt(1)
	v_mfma_f32_32x32x16_bf16 v[66:81], v[212:215], v[106:109], v[66:81]
	s_waitcnt lgkmcnt(0)
	v_mfma_f32_32x32x16_bf16 v[66:81], v[250:253], v[110:113], v[66:81]
	s_cbranch_scc1 .LBB0_192
	v_add_u32_e32 v1, 0xffffff80, v231
	v_cmp_gt_i32_e64 s[68:69], 26, v1
	v_cmp_gt_i32_e64 s[70:71], 27, v1
	v_cmp_gt_i32_e64 s[66:67], 25, v1
	s_and_b64 s[68:69], s[70:71], s[68:69]
	v_cmp_gt_i32_e64 s[64:65], 24, v1
	s_and_b64 s[66:67], s[68:69], s[66:67]
	v_cmp_gt_i32_e64 s[62:63], 19, v1
	s_and_b64 s[64:65], s[66:67], s[64:65]
	v_cmp_gt_i32_e64 s[60:61], 18, v1
	s_and_b64 s[62:63], s[64:65], s[62:63]
	v_cmp_gt_i32_e64 s[58:59], 17, v1
	s_and_b64 s[60:61], s[62:63], s[60:61]
	v_cmp_gt_i32_e64 s[56:57], 16, v1
	s_and_b64 s[58:59], s[60:61], s[58:59]
	v_cmp_gt_i32_e64 s[54:55], 11, v1
	s_and_b64 s[56:57], s[58:59], s[56:57]
	v_cmp_gt_i32_e64 s[52:53], 10, v1
	s_and_b64 s[54:55], s[56:57], s[54:55]
	v_cmp_gt_i32_e64 s[50:51], 9, v1
	s_and_b64 s[52:53], s[54:55], s[52:53]
	v_cmp_gt_i32_e64 s[48:49], 8, v1
	s_and_b64 s[50:51], s[52:53], s[50:51]
	v_cmp_gt_i32_e64 s[46:47], 3, v1
	s_and_b64 s[48:49], s[50:51], s[48:49]
	v_cmp_gt_i32_e64 s[44:45], 2, v1
	s_and_b64 s[46:47], s[48:49], s[46:47]
	v_cmp_gt_i32_e64 s[42:43], 1, v1
	s_and_b64 s[44:45], s[46:47], s[44:45]
	v_cmp_gt_i32_e64 s[40:41], 0, v1
	s_and_b64 s[42:43], s[44:45], s[42:43]
	s_and_b64 s[40:41], s[42:43], s[40:41]
	v_cmp_gt_i32_e64 s[36:37], 58, v1
	v_cndmask_b32_e64 v82, v82, v210, s[40:41]
	v_cmp_gt_i32_e64 s[40:41], 59, v1
	v_cmp_gt_i32_e64 s[34:35], 57, v1
	s_and_b64 s[36:37], s[40:41], s[36:37]
	v_cmp_gt_i32_e64 s[30:31], 56, v1
	s_and_b64 s[34:35], s[36:37], s[34:35]
	v_cmp_gt_i32_e64 s[28:29], 51, v1
	s_and_b64 s[30:31], s[34:35], s[30:31]
	v_cmp_gt_i32_e64 s[26:27], 50, v1
	s_and_b64 s[28:29], s[30:31], s[28:29]
	v_cmp_gt_i32_e64 s[24:25], 49, v1
	s_and_b64 s[26:27], s[28:29], s[26:27]
	v_cmp_gt_i32_e64 s[22:23], 48, v1
	s_and_b64 s[24:25], s[26:27], s[24:25]
	v_cmp_gt_i32_e64 s[20:21], 43, v1
	s_and_b64 s[22:23], s[24:25], s[22:23]
	v_cmp_gt_i32_e64 s[18:19], 42, v1
	s_and_b64 s[20:21], s[22:23], s[20:21]
	v_cmp_gt_i32_e64 s[16:17], 41, v1
	s_and_b64 s[18:19], s[20:21], s[18:19]
	v_cmp_gt_i32_e64 s[14:15], 40, v1
	s_and_b64 s[16:17], s[18:19], s[16:17]
	v_cmp_gt_i32_e64 s[12:13], 35, v1
	s_and_b64 s[14:15], s[16:17], s[14:15]
	v_cmp_gt_i32_e64 s[10:11], 34, v1
	s_and_b64 s[12:13], s[14:15], s[12:13]
	v_cmp_gt_i32_e64 s[8:9], 33, v1
	s_and_b64 s[10:11], s[12:13], s[10:11]
	v_cmp_gt_i32_e32 vcc, 32, v1
	s_and_b64 s[8:9], s[10:11], s[8:9]
	s_and_b64 vcc, s[8:9], vcc
	v_cndmask_b32_e64 v97, v97, v210, s[70:71]
	v_cndmask_b32_e64 v96, v96, v210, s[68:69]
	v_cndmask_b32_e64 v95, v95, v210, s[66:67]
	v_cndmask_b32_e64 v94, v94, v210, s[64:65]
	v_cndmask_b32_e64 v93, v93, v210, s[62:63]
	v_cndmask_b32_e64 v92, v92, v210, s[60:61]
	v_cndmask_b32_e64 v91, v91, v210, s[58:59]
	v_cndmask_b32_e64 v90, v90, v210, s[56:57]
	v_cndmask_b32_e64 v89, v89, v210, s[54:55]
	v_cndmask_b32_e64 v88, v88, v210, s[52:53]
	v_cndmask_b32_e64 v87, v87, v210, s[50:51]
	v_cndmask_b32_e64 v86, v86, v210, s[48:49]
	v_cndmask_b32_e64 v85, v85, v210, s[46:47]
	v_cndmask_b32_e64 v84, v84, v210, s[44:45]
	v_cndmask_b32_e64 v83, v83, v210, s[42:43]
	v_cndmask_b32_e64 v81, v81, v210, s[40:41]
	v_cndmask_b32_e64 v80, v80, v210, s[36:37]
	v_cndmask_b32_e64 v79, v79, v210, s[34:35]
	v_cndmask_b32_e64 v78, v78, v210, s[30:31]
	v_cndmask_b32_e64 v77, v77, v210, s[28:29]
	v_cndmask_b32_e64 v76, v76, v210, s[26:27]
	v_cndmask_b32_e64 v75, v75, v210, s[24:25]
	v_cndmask_b32_e64 v74, v74, v210, s[22:23]
	v_cndmask_b32_e64 v73, v73, v210, s[20:21]
	v_cndmask_b32_e64 v72, v72, v210, s[18:19]
	v_cndmask_b32_e64 v71, v71, v210, s[16:17]
	v_cndmask_b32_e64 v70, v70, v210, s[14:15]
	v_cndmask_b32_e64 v69, v69, v210, s[12:13]
	v_cndmask_b32_e64 v68, v68, v210, s[10:11]
	v_cndmask_b32_e64 v67, v67, v210, s[8:9]
	v_cndmask_b32_e32 v66, v66, v210, vcc

.LBB0_196:
	v_cndmask_b32_e64 v233, v234, v233, s[8:9]
	v_mul_f32_e32 v206, 0xbe38aa3b, v233
	v_fmamk_f32 v82, v82, 0x3e38aa3b, v206
	v_fmamk_f32 v83, v83, 0x3e38aa3b, v206
	v_fmamk_f32 v84, v84, 0x3e38aa3b, v206
	v_fmamk_f32 v85, v85, 0x3e38aa3b, v206
	v_fmamk_f32 v86, v86, 0x3e38aa3b, v206
	v_fmamk_f32 v87, v87, 0x3e38aa3b, v206
	v_fmamk_f32 v88, v88, 0x3e38aa3b, v206
	v_fmamk_f32 v89, v89, 0x3e38aa3b, v206
	v_fmamk_f32 v90, v90, 0x3e38aa3b, v206
	v_fmamk_f32 v91, v91, 0x3e38aa3b, v206
	v_fmamk_f32 v92, v92, 0x3e38aa3b, v206
	v_fmamk_f32 v93, v93, 0x3e38aa3b, v206
	v_fmamk_f32 v94, v94, 0x3e38aa3b, v206
	v_fmamk_f32 v95, v95, 0x3e38aa3b, v206
	v_fmamk_f32 v96, v96, 0x3e38aa3b, v206
	v_fmamk_f32 v97, v97, 0x3e38aa3b, v206
	v_fmamk_f32 v66, v66, 0x3e38aa3b, v206
	v_fmamk_f32 v67, v67, 0x3e38aa3b, v206
	v_fmamk_f32 v68, v68, 0x3e38aa3b, v206
	v_fmamk_f32 v69, v69, 0x3e38aa3b, v206
	v_fmamk_f32 v70, v70, 0x3e38aa3b, v206
	v_fmamk_f32 v71, v71, 0x3e38aa3b, v206
	v_fmamk_f32 v72, v72, 0x3e38aa3b, v206
	v_fmamk_f32 v73, v73, 0x3e38aa3b, v206
	v_fmamk_f32 v74, v74, 0x3e38aa3b, v206
	v_fmamk_f32 v75, v75, 0x3e38aa3b, v206
	v_fmamk_f32 v76, v76, 0x3e38aa3b, v206
	v_fmamk_f32 v77, v77, 0x3e38aa3b, v206
	v_fmamk_f32 v78, v78, 0x3e38aa3b, v206
	v_fmamk_f32 v79, v79, 0x3e38aa3b, v206
	v_fmamk_f32 v80, v80, 0x3e38aa3b, v206
	v_fmac_f32_e32 v206, 0x3e38aa3b, v81
	v_exp_f32_e32 v81, v82
	v_exp_f32_e32 v82, v83
	v_exp_f32_e32 v83, v84
	v_exp_f32_e32 v84, v85
	v_exp_f32_e32 v85, v86
	v_exp_f32_e32 v86, v87
	v_exp_f32_e32 v87, v88
	v_exp_f32_e32 v88, v89
	v_exp_f32_e32 v89, v90
	v_exp_f32_e32 v90, v91
	v_exp_f32_e32 v91, v92
	v_exp_f32_e32 v92, v93
	v_exp_f32_e32 v93, v94
	v_exp_f32_e32 v94, v95
	v_exp_f32_e32 v95, v96
	v_exp_f32_e32 v96, v97
	v_exp_f32_e32 v97, v66
	v_add_f32_e32 v66, 0, v81
	v_add_f32_e32 v66, v82, v66
	v_add_f32_e32 v66, v83, v66
	v_add_f32_e32 v66, v84, v66
	v_add_f32_e32 v66, v85, v66
	v_add_f32_e32 v66, v86, v66
	v_add_f32_e32 v66, v87, v66
	v_add_f32_e32 v66, v88, v66
	v_add_f32_e32 v66, v89, v66
	v_add_f32_e32 v66, v90, v66
	v_add_f32_e32 v66, v91, v66
	v_add_f32_e32 v66, v92, v66
	v_add_f32_e32 v66, v93, v66
	v_exp_f32_e32 v212, v67
	v_add_f32_e32 v66, v94, v66
	v_exp_f32_e32 v213, v68
	v_add_f32_e32 v66, v95, v66
	v_exp_f32_e32 v214, v69
	v_add_f32_e32 v66, v96, v66
	v_exp_f32_e32 v215, v70
	v_add_f32_e32 v66, v97, v66
	v_exp_f32_e32 v236, v71
	v_add_f32_e32 v66, v212, v66
	v_exp_f32_e32 v237, v72
	v_add_f32_e32 v66, v213, v66
	v_exp_f32_e32 v238, v73
	v_add_f32_e32 v66, v214, v66
	v_exp_f32_e32 v239, v74
	v_add_f32_e32 v66, v215, v66
	v_exp_f32_e32 v240, v75
	v_add_f32_e32 v66, v236, v66
	v_exp_f32_e32 v241, v76
	v_add_f32_e32 v66, v237, v66
	v_exp_f32_e32 v242, v77
	v_add_f32_e32 v66, v238, v66
	v_exp_f32_e32 v243, v78
	v_add_f32_e32 v66, v239, v66
	v_exp_f32_e32 v244, v79
	v_add_f32_e32 v66, v240, v66
	v_exp_f32_e32 v245, v80
	v_add_f32_e32 v66, v241, v66
	v_exp_f32_e32 v206, v206
	v_add_f32_e32 v66, v242, v66
	v_add_f32_e32 v66, v243, v66
	v_add_f32_e32 v66, v244, v66
	v_add_f32_e32 v66, v245, v66
	v_add_f32_e32 v234, v206, v66
	v_mov_b32_e32 v235, v234
	s_nop 1
	v_permlane32_swap_b32_e32 v234, v235
	v_cvt_pk_bf16_f32 v66, v81, v82
	v_cvt_pk_bf16_f32 v67, v83, v84
	v_cvt_pk_bf16_f32 v68, v85, v86
	v_cvt_pk_bf16_f32 v69, v87, v88
	v_cvt_pk_bf16_f32 v70, v89, v90
	v_cvt_pk_bf16_f32 v71, v91, v92
	v_cvt_pk_bf16_f32 v72, v93, v94
	v_cvt_pk_bf16_f32 v73, v95, v96
	v_cvt_pk_bf16_f32 v74, v97, v212
	ds_read_b64_tr_b16 v[82:83], v153 offset:0x8000
	ds_read_b64_tr_b16 v[84:85], v153 offset:0x8800
	ds_read_b64_tr_b16 v[86:87], v153 offset:0x9000
	ds_read_b64_tr_b16 v[88:89], v153 offset:0x9800
	ds_read_b64_tr_b16 v[90:91], v153 offset:0xa000
	ds_read_b64_tr_b16 v[92:93], v153 offset:0xa800
	ds_read_b64_tr_b16 v[94:95], v153 offset:0xb000
	ds_read_b64_tr_b16 v[96:97], v153 offset:0xb800
	v_cvt_pk_bf16_f32 v75, v213, v214
	v_cvt_pk_bf16_f32 v76, v215, v236
	v_cvt_pk_bf16_f32 v77, v237, v238
	v_cvt_pk_bf16_f32 v78, v239, v240
	v_cvt_pk_bf16_f32 v79, v241, v242
	v_cvt_pk_bf16_f32 v80, v243, v244
	v_cvt_pk_bf16_f32 v81, v245, v206
	s_nop 0
	v_permlane32_swap_b32_e32 v66, v68
	v_permlane32_swap_b32_e32 v67, v69
	v_permlane32_swap_b32_e32 v70, v72
	v_permlane32_swap_b32_e32 v71, v73
	v_permlane32_swap_b32_e32 v74, v76
	v_permlane32_swap_b32_e32 v75, v77
	v_permlane32_swap_b32_e32 v78, v80
	v_permlane32_swap_b32_e32 v79, v81
	s_nop 0
	s_waitcnt lgkmcnt(6)
	v_mfma_f32_32x32x16_bf16 v[50:65], v[66:69], v[82:85], v[50:65]
	ds_read_b64_tr_b16 v[82:83], v153 offset:0x8200
	ds_read_b64_tr_b16 v[84:85], v153 offset:0x8a00
	s_waitcnt lgkmcnt(6)
	v_mfma_f32_32x32x16_bf16 v[50:65], v[70:73], v[86:89], v[50:65]
	ds_read_b64_tr_b16 v[86:87], v153 offset:0x9200
	ds_read_b64_tr_b16 v[88:89], v153 offset:0x9a00
	s_waitcnt lgkmcnt(6)
	v_mfma_f32_32x32x16_bf16 v[50:65], v[74:77], v[90:93], v[50:65]
	ds_read_b64_tr_b16 v[90:91], v153 offset:0xa200
	ds_read_b64_tr_b16 v[92:93], v153 offset:0xaa00
	s_waitcnt lgkmcnt(6)
	v_mfma_f32_32x32x16_bf16 v[50:65], v[78:81], v[94:97], v[50:65]
	s_andn2_b64 vcc, exec, s[72:73]
	s_cbranch_vccnz .Lattn_sw2
	s_waitcnt vmcnt(3)
	ds_write_b128 v224, v[114:117]
	s_waitcnt vmcnt(1)
	ds_write_b128 v224, v[122:125] offset:8192
	ds_write_b128 v173, v[118:121]
	s_waitcnt vmcnt(0)
	ds_write_b128 v175, v[126:129]

.Lattn_sl2:
	ds_read_b64_tr_b16 v[94:95], v153 offset:0xb200
	ds_read_b64_tr_b16 v[96:97], v153 offset:0xba00
	s_waitcnt lgkmcnt(6)
	v_mfma_f32_32x32x16_bf16 v[34:49], v[66:69], v[82:85], v[34:49]
	ds_read_b64_tr_b16 v[82:83], v153 offset:0x8400
	ds_read_b64_tr_b16 v[84:85], v153 offset:0x8c00
	s_waitcnt lgkmcnt(6)
	v_mfma_f32_32x32x16_bf16 v[34:49], v[70:73], v[86:89], v[34:49]
	ds_read_b64_tr_b16 v[86:87], v153 offset:0x9400
	ds_read_b64_tr_b16 v[88:89], v153 offset:0x9c00
	s_waitcnt lgkmcnt(6)
	v_mfma_f32_32x32x16_bf16 v[34:49], v[74:77], v[90:93], v[34:49]
	ds_read_b64_tr_b16 v[90:91], v153 offset:0xa400
	ds_read_b64_tr_b16 v[92:93], v153 offset:0xac00
	s_waitcnt lgkmcnt(6)
	v_mfma_f32_32x32x16_bf16 v[34:49], v[78:81], v[94:97], v[34:49]
	ds_read_b64_tr_b16 v[94:95], v153 offset:0xb400
	ds_read_b64_tr_b16 v[96:97], v153 offset:0xbc00
	s_waitcnt lgkmcnt(6)
	v_mfma_f32_32x32x16_bf16 v[18:33], v[66:69], v[82:85], v[18:33]
	ds_read_b64_tr_b16 v[82:83], v153 offset:0x8600
	ds_read_b64_tr_b16 v[84:85], v153 offset:0x8e00
	s_waitcnt lgkmcnt(6)
	v_mfma_f32_32x32x16_bf16 v[18:33], v[70:73], v[86:89], v[18:33]
	ds_read_b64_tr_b16 v[86:87], v153 offset:0x9600
	ds_read_b64_tr_b16 v[88:89], v153 offset:0x9e00
	s_waitcnt lgkmcnt(6)
	v_mfma_f32_32x32x16_bf16 v[18:33], v[74:77], v[90:93], v[18:33]
	ds_read_b64_tr_b16 v[90:91], v153 offset:0xa600
	ds_read_b64_tr_b16 v[92:93], v153 offset:0xae00
	s_waitcnt lgkmcnt(6)
	v_mfma_f32_32x32x16_bf16 v[18:33], v[78:81], v[94:97], v[18:33]
	ds_read_b64_tr_b16 v[94:95], v153 offset:0xb600
	ds_read_b64_tr_b16 v[96:97], v153 offset:0xbe00
	s_waitcnt lgkmcnt(6)
	v_mfma_f32_32x32x16_bf16 v[2:17], v[66:69], v[82:85], v[2:17]
	s_andn2_b64 vcc, exec, s[38:39]
	ds_read_b128 v[66:69], v225 offset:49152
	s_waitcnt lgkmcnt(5)
	v_mfma_f32_32x32x16_bf16 v[2:17], v[70:73], v[86:89], v[2:17]
	ds_read_b128 v[70:73], v226 offset:49152
	s_waitcnt lgkmcnt(4)
	v_mfma_f32_32x32x16_bf16 v[2:17], v[74:77], v[90:93], v[2:17]
	ds_read_b128 v[74:77], v227 offset:49152
	s_waitcnt lgkmcnt(3)
	v_mfma_f32_32x32x16_bf16 v[2:17], v[78:81], v[94:97], v[2:17]
	ds_read_b128 v[78:81], v228 offset:49152
	ds_read_b128 v[212:215], v225 offset:57344
	ds_read_b128 v[250:253], v226 offset:57344
.LBB0_200:
	s_cmp_le_i32 s98, s74
	s_waitcnt lgkmcnt(5)
	v_mfma_f32_32x32x16_bf16 v[82:97], v[66:69], v[98:101], 0
	s_waitcnt lgkmcnt(4)
	v_mfma_f32_32x32x16_bf16 v[82:97], v[70:73], v[102:105], v[82:97]
	s_waitcnt lgkmcnt(3)
	v_mfma_f32_32x32x16_bf16 v[82:97], v[74:77], v[106:109], v[82:97]
	s_waitcnt lgkmcnt(2)
	v_mfma_f32_32x32x16_bf16 v[82:97], v[78:81], v[110:113], v[82:97]
	s_waitcnt lgkmcnt(1)
	v_mfma_f32_32x32x16_bf16 v[66:81], v[212:215], v[98:101], 0
	ds_read_b128 v[212:215], v227 offset:57344
	s_waitcnt lgkmcnt(1)
	v_mfma_f32_32x32x16_bf16 v[66:81], v[250:253], v[102:105], v[66:81]
	ds_read_b128 v[250:253], v228 offset:57344
	s_waitcnt lgkmcnt(1)
	v_mfma_f32_32x32x16_bf16 v[66:81], v[212:215], v[106:109], v[66:81]
	s_waitcnt lgkmcnt(0)
	v_mfma_f32_32x32x16_bf16 v[66:81], v[250:253], v[110:113], v[66:81]
	s_cbranch_scc1 .LBB0_202
	v_add_u32_e32 v206, 0xffffff40, v231
	v_cmp_gt_i32_e64 s[68:69], 26, v206
	v_cmp_gt_i32_e64 s[70:71], 27, v206
	v_cmp_gt_i32_e64 s[66:67], 25, v206
	s_and_b64 s[68:69], s[70:71], s[68:69]
	v_cmp_gt_i32_e64 s[64:65], 24, v206
	s_and_b64 s[66:67], s[68:69], s[66:67]
	v_cmp_gt_i32_e64 s[62:63], 19, v206
	s_and_b64 s[64:65], s[66:67], s[64:65]
	v_cmp_gt_i32_e64 s[60:61], 18, v206
	s_and_b64 s[62:63], s[64:65], s[62:63]
	v_cmp_gt_i32_e64 s[58:59], 17, v206
	s_and_b64 s[60:61], s[62:63], s[60:61]
	v_cmp_gt_i32_e64 s[56:57], 16, v206
	s_and_b64 s[58:59], s[60:61], s[58:59]
	v_cmp_gt_i32_e64 s[54:55], 11, v206
	s_and_b64 s[56:57], s[58:59], s[56:57]
	v_cmp_gt_i32_e64 s[52:53], 10, v206
	s_and_b64 s[54:55], s[56:57], s[54:55]
	v_cmp_gt_i32_e64 s[50:51], 9, v206
	s_and_b64 s[52:53], s[54:55], s[52:53]
	v_cmp_gt_i32_e64 s[48:49], 8, v206
	s_and_b64 s[50:51], s[52:53], s[50:51]
	v_cmp_gt_i32_e64 s[46:47], 3, v206
	s_and_b64 s[48:49], s[50:51], s[48:49]
	v_cmp_gt_i32_e64 s[44:45], 2, v206
	s_and_b64 s[46:47], s[48:49], s[46:47]
	v_cmp_gt_i32_e64 s[42:43], 1, v206
	s_and_b64 s[44:45], s[46:47], s[44:45]
	v_cmp_gt_i32_e64 s[40:41], 0, v206
	s_and_b64 s[42:43], s[44:45], s[42:43]
	s_and_b64 s[40:41], s[42:43], s[40:41]
	v_cmp_gt_i32_e64 s[36:37], 58, v206
	v_cndmask_b32_e64 v82, v82, v210, s[40:41]
	v_cmp_gt_i32_e64 s[40:41], 59, v206
	v_cmp_gt_i32_e64 s[34:35], 57, v206
	s_and_b64 s[36:37], s[40:41], s[36:37]
	v_cmp_gt_i32_e64 s[30:31], 56, v206
	s_and_b64 s[34:35], s[36:37], s[34:35]
	v_cmp_gt_i32_e64 s[28:29], 51, v206
	s_and_b64 s[30:31], s[34:35], s[30:31]
	v_cmp_gt_i32_e64 s[26:27], 50, v206
	s_and_b64 s[28:29], s[30:31], s[28:29]
	v_cmp_gt_i32_e64 s[24:25], 49, v206
	s_and_b64 s[26:27], s[28:29], s[26:27]
	v_cmp_gt_i32_e64 s[22:23], 48, v206
	s_and_b64 s[24:25], s[26:27], s[24:25]
	v_cmp_gt_i32_e64 s[20:21], 43, v206
	s_and_b64 s[22:23], s[24:25], s[22:23]
	v_cmp_gt_i32_e64 s[18:19], 42, v206
	s_and_b64 s[20:21], s[22:23], s[20:21]
	v_cmp_gt_i32_e64 s[16:17], 41, v206
	s_and_b64 s[18:19], s[20:21], s[18:19]
	v_cmp_gt_i32_e64 s[14:15], 40, v206
	s_and_b64 s[16:17], s[18:19], s[16:17]
	v_cmp_gt_i32_e64 s[12:13], 35, v206
	s_and_b64 s[14:15], s[16:17], s[14:15]
	v_cmp_gt_i32_e64 s[10:11], 34, v206
	s_and_b64 s[12:13], s[14:15], s[12:13]
	v_cmp_gt_i32_e64 s[8:9], 33, v206
	s_and_b64 s[10:11], s[12:13], s[10:11]
	v_cmp_gt_i32_e32 vcc, 32, v206
	s_and_b64 s[8:9], s[10:11], s[8:9]
	s_and_b64 vcc, s[8:9], vcc
	v_cndmask_b32_e64 v97, v97, v210, s[70:71]
	v_cndmask_b32_e64 v96, v96, v210, s[68:69]
	v_cndmask_b32_e64 v95, v95, v210, s[66:67]
	v_cndmask_b32_e64 v94, v94, v210, s[64:65]
	v_cndmask_b32_e64 v93, v93, v210, s[62:63]
	v_cndmask_b32_e64 v92, v92, v210, s[60:61]
	v_cndmask_b32_e64 v91, v91, v210, s[58:59]
	v_cndmask_b32_e64 v90, v90, v210, s[56:57]
	v_cndmask_b32_e64 v89, v89, v210, s[54:55]
	v_cndmask_b32_e64 v88, v88, v210, s[52:53]
	v_cndmask_b32_e64 v87, v87, v210, s[50:51]
	v_cndmask_b32_e64 v86, v86, v210, s[48:49]
	v_cndmask_b32_e64 v85, v85, v210, s[46:47]
	v_cndmask_b32_e64 v84, v84, v210, s[44:45]
	v_cndmask_b32_e64 v83, v83, v210, s[42:43]
	v_cndmask_b32_e64 v81, v81, v210, s[40:41]
	v_cndmask_b32_e64 v80, v80, v210, s[36:37]
	v_cndmask_b32_e64 v79, v79, v210, s[34:35]
	v_cndmask_b32_e64 v78, v78, v210, s[30:31]
	v_cndmask_b32_e64 v77, v77, v210, s[28:29]
	v_cndmask_b32_e64 v76, v76, v210, s[26:27]
	v_cndmask_b32_e64 v75, v75, v210, s[24:25]
	v_cndmask_b32_e64 v74, v74, v210, s[22:23]
	v_cndmask_b32_e64 v73, v73, v210, s[20:21]
	v_cndmask_b32_e64 v72, v72, v210, s[18:19]
	v_cndmask_b32_e64 v71, v71, v210, s[16:17]
	v_cndmask_b32_e64 v70, v70, v210, s[14:15]
	v_cndmask_b32_e64 v69, v69, v210, s[12:13]
	v_cndmask_b32_e64 v68, v68, v210, s[10:11]
	v_cndmask_b32_e64 v67, v67, v210, s[8:9]
	v_cndmask_b32_e32 v66, v66, v210, vcc

.LBB0_206:
	v_cndmask_b32_e64 v233, v237, v233, s[8:9]
	v_mul_f32_e32 v206, 0xbe38aa3b, v233
	v_fmamk_f32 v82, v82, 0x3e38aa3b, v206
	v_fmamk_f32 v83, v83, 0x3e38aa3b, v206
	v_fmamk_f32 v84, v84, 0x3e38aa3b, v206
	v_fmamk_f32 v85, v85, 0x3e38aa3b, v206
	v_fmamk_f32 v86, v86, 0x3e38aa3b, v206
	v_fmamk_f32 v87, v87, 0x3e38aa3b, v206
	v_fmamk_f32 v88, v88, 0x3e38aa3b, v206
	v_fmamk_f32 v89, v89, 0x3e38aa3b, v206
	v_fmamk_f32 v90, v90, 0x3e38aa3b, v206
	v_fmamk_f32 v91, v91, 0x3e38aa3b, v206
	v_fmamk_f32 v92, v92, 0x3e38aa3b, v206
	v_fmamk_f32 v93, v93, 0x3e38aa3b, v206
	v_fmamk_f32 v94, v94, 0x3e38aa3b, v206
	v_fmamk_f32 v95, v95, 0x3e38aa3b, v206
	v_fmamk_f32 v96, v96, 0x3e38aa3b, v206
	v_fmamk_f32 v97, v97, 0x3e38aa3b, v206
	v_fmamk_f32 v66, v66, 0x3e38aa3b, v206
	v_fmamk_f32 v67, v67, 0x3e38aa3b, v206
	v_fmamk_f32 v68, v68, 0x3e38aa3b, v206
	v_fmamk_f32 v69, v69, 0x3e38aa3b, v206
	v_fmamk_f32 v70, v70, 0x3e38aa3b, v206
	v_fmamk_f32 v71, v71, 0x3e38aa3b, v206
	v_fmamk_f32 v72, v72, 0x3e38aa3b, v206
	v_fmamk_f32 v73, v73, 0x3e38aa3b, v206
	v_fmamk_f32 v74, v74, 0x3e38aa3b, v206
	v_fmamk_f32 v75, v75, 0x3e38aa3b, v206
	v_fmamk_f32 v76, v76, 0x3e38aa3b, v206
	v_fmamk_f32 v77, v77, 0x3e38aa3b, v206
	v_fmamk_f32 v78, v78, 0x3e38aa3b, v206
	v_fmamk_f32 v79, v79, 0x3e38aa3b, v206
	v_fmamk_f32 v80, v80, 0x3e38aa3b, v206
	v_fmac_f32_e32 v206, 0x3e38aa3b, v81
	v_exp_f32_e32 v81, v82
	v_exp_f32_e32 v82, v83
	v_exp_f32_e32 v83, v84
	v_exp_f32_e32 v84, v85
	v_exp_f32_e32 v85, v86
	v_exp_f32_e32 v86, v87
	v_exp_f32_e32 v87, v88
	v_exp_f32_e32 v88, v89
	v_exp_f32_e32 v89, v90
	v_exp_f32_e32 v90, v91
	v_exp_f32_e32 v91, v92
	v_exp_f32_e32 v92, v93
	v_exp_f32_e32 v93, v94
	v_exp_f32_e32 v94, v95
	v_exp_f32_e32 v95, v96
	v_exp_f32_e32 v96, v97
	v_add_f32_e32 v97, v234, v235
	v_fmac_f32_e32 v97, v232, v1
	v_exp_f32_e32 v1, v66
	v_add_f32_e32 v66, 0, v81
	v_add_f32_e32 v66, v82, v66
	v_add_f32_e32 v66, v83, v66
	v_add_f32_e32 v66, v84, v66
	v_add_f32_e32 v66, v85, v66
	v_add_f32_e32 v66, v86, v66
	v_add_f32_e32 v66, v87, v66
	v_add_f32_e32 v66, v88, v66
	v_add_f32_e32 v66, v89, v66
	v_add_f32_e32 v66, v90, v66
	v_add_f32_e32 v66, v91, v66
	v_add_f32_e32 v66, v92, v66
	v_add_f32_e32 v66, v93, v66
	v_exp_f32_e32 v212, v67
	v_add_f32_e32 v66, v94, v66
	v_exp_f32_e32 v213, v68
	v_add_f32_e32 v66, v95, v66
	v_exp_f32_e32 v214, v69
	v_add_f32_e32 v66, v96, v66
	v_exp_f32_e32 v215, v70
	v_add_f32_e32 v66, v1, v66
	v_exp_f32_e32 v234, v71
	v_add_f32_e32 v66, v212, v66
	v_exp_f32_e32 v235, v72
	v_add_f32_e32 v66, v213, v66
	v_exp_f32_e32 v237, v73
	v_add_f32_e32 v66, v214, v66
	v_exp_f32_e32 v238, v74
	v_add_f32_e32 v66, v215, v66
	v_exp_f32_e32 v239, v75
	v_add_f32_e32 v66, v234, v66
	v_exp_f32_e32 v240, v76
	v_add_f32_e32 v66, v235, v66
	v_exp_f32_e32 v241, v77
	v_add_f32_e32 v66, v237, v66
	v_exp_f32_e32 v242, v78
	v_add_f32_e32 v66, v238, v66
	v_exp_f32_e32 v243, v79
	v_add_f32_e32 v66, v239, v66
	v_exp_f32_e32 v244, v80
	v_add_f32_e32 v66, v240, v66
	v_exp_f32_e32 v206, v206
	v_add_f32_e32 v66, v241, v66
	v_add_f32_e32 v66, v242, v66
	v_add_f32_e32 v66, v243, v66
	v_add_f32_e32 v66, v244, v66
	v_add_f32_e32 v66, v206, v66
	v_mov_b32_e32 v67, v66
	s_nop 1
	v_permlane32_swap_b32_e32 v66, v67
	v_add_f32_e32 v232, v66, v67
	v_fmac_f32_e32 v232, v97, v236
	v_cvt_pk_bf16_f32 v66, v81, v82
	v_cvt_pk_bf16_f32 v67, v83, v84
	v_cvt_pk_bf16_f32 v68, v85, v86
	v_cvt_pk_bf16_f32 v69, v87, v88
	v_cvt_pk_bf16_f32 v70, v89, v90
	v_cvt_pk_bf16_f32 v71, v91, v92
	v_cvt_pk_bf16_f32 v72, v93, v94
	v_cvt_pk_bf16_f32 v73, v95, v96
	ds_read_b64_tr_b16 v[82:83], v153 offset:0xc000
	ds_read_b64_tr_b16 v[84:85], v153 offset:0xc800
	ds_read_b64_tr_b16 v[86:87], v153 offset:0xd000
	ds_read_b64_tr_b16 v[88:89], v153 offset:0xd800
	ds_read_b64_tr_b16 v[90:91], v153 offset:0xe000
	ds_read_b64_tr_b16 v[92:93], v153 offset:0xe800
	ds_read_b64_tr_b16 v[94:95], v153 offset:0xf000
	ds_read_b64_tr_b16 v[96:97], v153 offset:0xf800
	v_cvt_pk_bf16_f32 v74, v1, v212
	v_cvt_pk_bf16_f32 v75, v213, v214
	v_cvt_pk_bf16_f32 v76, v215, v234
	v_cvt_pk_bf16_f32 v77, v235, v237
	v_cvt_pk_bf16_f32 v78, v238, v239
	v_cvt_pk_bf16_f32 v79, v240, v241
	v_cvt_pk_bf16_f32 v80, v242, v243
	v_cvt_pk_bf16_f32 v81, v244, v206
	s_nop 0
	v_permlane32_swap_b32_e32 v66, v68
	v_permlane32_swap_b32_e32 v67, v69
	v_permlane32_swap_b32_e32 v70, v72
	v_permlane32_swap_b32_e32 v71, v73
	v_permlane32_swap_b32_e32 v74, v76
	v_permlane32_swap_b32_e32 v75, v77
	v_permlane32_swap_b32_e32 v78, v80
	v_permlane32_swap_b32_e32 v79, v81
	s_nop 0
	s_waitcnt lgkmcnt(6)
	v_mfma_f32_32x32x16_bf16 v[50:65], v[66:69], v[82:85], v[50:65]
	ds_read_b64_tr_b16 v[82:83], v153 offset:0xc200
	ds_read_b64_tr_b16 v[84:85], v153 offset:0xca00
	s_waitcnt lgkmcnt(6)
	v_mfma_f32_32x32x16_bf16 v[50:65], v[70:73], v[86:89], v[50:65]
	ds_read_b64_tr_b16 v[86:87], v153 offset:0xd200
	ds_read_b64_tr_b16 v[88:89], v153 offset:0xda00
	s_waitcnt lgkmcnt(6)
	v_mfma_f32_32x32x16_bf16 v[50:65], v[74:77], v[90:93], v[50:65]
	ds_read_b64_tr_b16 v[90:91], v153 offset:0xe200
	ds_read_b64_tr_b16 v[92:93], v153 offset:0xea00
	s_waitcnt lgkmcnt(6)
	v_mfma_f32_32x32x16_bf16 v[50:65], v[78:81], v[94:97], v[50:65]
	s_andn2_b64 vcc, exec, s[38:39]
	s_cbranch_vccnz .Lattn_sw3
	s_waitcnt vmcnt(3)
	ds_write_b128 v224, v[114:117] offset:16384
	s_waitcnt vmcnt(1)
	ds_write_b128 v224, v[122:125] offset:24576
	ds_write_b128 v229, v[118:121]
	s_waitcnt vmcnt(0)
	ds_write_b128 v230, v[126:129]

.Lattn_sl3:
	ds_read_b64_tr_b16 v[94:95], v153 offset:0xf200
	ds_read_b64_tr_b16 v[96:97], v153 offset:0xfa00
	s_waitcnt lgkmcnt(6)
	v_mfma_f32_32x32x16_bf16 v[34:49], v[66:69], v[82:85], v[34:49]
	ds_read_b64_tr_b16 v[82:83], v153 offset:0xc400
	ds_read_b64_tr_b16 v[84:85], v153 offset:0xcc00
	s_waitcnt lgkmcnt(6)
	v_mfma_f32_32x32x16_bf16 v[34:49], v[70:73], v[86:89], v[34:49]
	ds_read_b64_tr_b16 v[86:87], v153 offset:0xd400
	ds_read_b64_tr_b16 v[88:89], v153 offset:0xdc00
	s_waitcnt lgkmcnt(6)
	v_mfma_f32_32x32x16_bf16 v[34:49], v[74:77], v[90:93], v[34:49]
	ds_read_b64_tr_b16 v[90:91], v153 offset:0xe400
	ds_read_b64_tr_b16 v[92:93], v153 offset:0xec00
	s_waitcnt lgkmcnt(6)
	v_mfma_f32_32x32x16_bf16 v[34:49], v[78:81], v[94:97], v[34:49]
	ds_read_b64_tr_b16 v[94:95], v153 offset:0xf400
	ds_read_b64_tr_b16 v[96:97], v153 offset:0xfc00
	s_waitcnt lgkmcnt(6)
	v_mfma_f32_32x32x16_bf16 v[18:33], v[66:69], v[82:85], v[18:33]
	ds_read_b64_tr_b16 v[82:83], v153 offset:0xc600
	ds_read_b64_tr_b16 v[84:85], v153 offset:0xce00
	s_waitcnt lgkmcnt(6)
	v_mfma_f32_32x32x16_bf16 v[18:33], v[70:73], v[86:89], v[18:33]
	ds_read_b64_tr_b16 v[86:87], v153 offset:0xd600
	ds_read_b64_tr_b16 v[88:89], v153 offset:0xde00
	s_waitcnt lgkmcnt(6)
	v_mfma_f32_32x32x16_bf16 v[18:33], v[74:77], v[90:93], v[18:33]
	ds_read_b64_tr_b16 v[90:91], v153 offset:0xe600
	ds_read_b64_tr_b16 v[92:93], v153 offset:0xee00
	s_waitcnt lgkmcnt(6)
	v_mfma_f32_32x32x16_bf16 v[18:33], v[78:81], v[94:97], v[18:33]
	ds_read_b64_tr_b16 v[94:95], v153 offset:0xf600
	ds_read_b64_tr_b16 v[96:97], v153 offset:0xfe00
	s_waitcnt lgkmcnt(6)
	v_mfma_f32_32x32x16_bf16 v[2:17], v[66:69], v[82:85], v[2:17]
	s_waitcnt lgkmcnt(0)
	s_barrier
	ds_read_b128 v[66:69], v225
	v_mfma_f32_32x32x16_bf16 v[2:17], v[70:73], v[86:89], v[2:17]
	ds_read_b128 v[70:73], v226
	v_mfma_f32_32x32x16_bf16 v[2:17], v[74:77], v[90:93], v[2:17]
	ds_read_b128 v[74:77], v227
	v_mfma_f32_32x32x16_bf16 v[2:17], v[78:81], v[94:97], v[2:17]
	ds_read_b128 v[78:81], v228
	ds_read_b128 v[212:215], v225 offset:8192
	ds_read_b128 v[250:253], v226 offset:8192
